# v8: v4 + P2 epilogue: x loads prefetched 8 ahead, the 8 row-sum atomics kept in registers and issued together at the end
# speedup vs baseline: 1.0029x; 1.0029x over previous
; __host__ __device__ __forceinline__ size_t blk(int r, int k, int K) { return (((size_t)((r >> 8) * (K >> 6) + (k >> 6))) << 14) + (size_t)(((r & 255) << 6) + (k & 63)); }
; __device__ __forceinline__ float bflo(unsigned w) { return __uint_as_float(w << 16); }
; __device__ __forceinline__ float bfhi(unsigned w) { return __uint_as_float(w & 0xffff0000u); }
; __device__ __forceinline__ unsigned pk2(float lo, float hi) { f32x2 v = {lo, hi}; bf16x2_t b = __builtin_convertvector(v, bf16x2_t); return __builtin_bit_cast(unsigned, b); }
;     __device__ __forceinline__ void operator()(const f32x4 (&acc)[2][2][4][2], const Unit& u, int wr, int wc, int fr, int fq) const {
;         const int row0 = u.pm * BM + wr * 64 + fr, col0 = u.pn * BM + wc * 32 + 8 * fq;
; #pragma unroll
;         for (int ai = 0; ai < 2; ++ai)
; #pragma unroll
;             for (int m = 0; m < 4; ++m) { const int row = row0 + ai * HALF + m * 16; const size_t off = (size_t)row * D + col0; float s = 0.f;
; #pragma unroll
;                 for (int bj = 0; bj < 2; ++bj) {
;                     f32x4 v0, v1;
;                     if (MODE == 0) { v0 = *(const f32x4*)(base + off + bj * HALF); v1 = *(const f32x4*)(base + off + bj * HALF + 4); }
;                     else { const u32x4 r = *(const u32x4*)(bb + blk(row, col0 + bj * HALF, D)); v0 = (f32x4){bflo(r.x), bfhi(r.x), bflo(r.y), bfhi(r.y)}; v1 = (f32x4){bflo(r.z), bfhi(r.z), bflo(r.w), bfhi(r.w)}; }
;                     v0 += acc[ai][bj][m][0] * alpha; v1 += acc[ai][bj][m][1] * alpha;
;                     if (MODE == 2) { *(f32x4*)(out + off + bj * HALF) = v0; *(f32x4*)(out + off + bj * HALF + 4) = v1; }
;                     else {
;                         s += (v0[0] * v0[0] + v0[1] * v0[1]) + (v0[2] * v0[2] + v0[3] * v0[3]) + (v1[0] * v1[0] + v1[1] * v1[1]) + (v1[2] * v1[2] + v1[3] * v1[3]);
;                         u32x4 w; w.x = pk2(v0[0], v0[1]); w.y = pk2(v0[2], v0[3]); w.z = pk2(v1[0], v1[1]); w.w = pk2(v1[2], v1[3]); *(u32x4*)(xb + blk(row, col0 + bj * HALF, D)) = w; } }
;                 if (MODE != 2) { s += __shfl_xor(s, 16); s += __shfl_xor(s, 32); if (fq == 0) unsafeAtomicAdd(ssq + row, s); } }
.LBB0_203:
	s_lshl_b32 s44, s73, 8
	s_add_i32 s44, s44, s35
	v_or_b32_e32 v150, s44, v1
	s_lshl_b32 s45, s72, 8
	s_or_b32 s45, s45, s56
	v_ashrrev_i32_e32 v151, 31, v150
	v_or_b32_e32 v148, s45, v152
	v_lshlrev_b64 v[158:159], 14, v[150:151]
	v_ashrrev_i32_e32 v149, 31, v148
	v_lshl_add_u64 v[158:159], s[8:9], 0, v[158:159]
	v_lshl_add_u64 v[168:169], v[148:149], 2, v[158:159]
	v_mov_b32_e32 v176, v168
	v_mov_b32_e32 v177, v169
	global_load_dwordx4 v[160:163], v[168:169], off
	global_load_dwordx4 v[164:167], v[168:169], off offset:16
	s_mov_b32 s98, 0x40000
	s_mov_b32 s99, 0
	s_mov_b32 s100, 0x140000
	s_mov_b32 s101, 0
	global_load_dwordx4 v[172:175], v[176:177], off offset:512
	global_load_dwordx4 v[180:183], v[176:177], off offset:528
	v_lshl_add_u64 v[176:177], v[176:177], 0, s[98:99]
	global_load_dwordx4 v[184:187], v[176:177], off
	global_load_dwordx4 v[188:191], v[176:177], off offset:16
	global_load_dwordx4 v[196:199], v[176:177], off offset:512
	global_load_dwordx4 v[200:203], v[176:177], off offset:528
	v_lshl_add_u64 v[176:177], v[176:177], 0, s[98:99]
	global_load_dwordx4 v[204:207], v[176:177], off
	global_load_dwordx4 v[208:211], v[176:177], off offset:16
	s_ashr_i32 s44, s44, 2
	s_ashr_i32 s50, s45, 6
	s_and_b32 s46, s44, 0xffffffc0
	s_add_i32 s44, s46, s50
	v_bitop3_b32 v158, s45, 56, v152 bitop3:0xc8
	s_ashr_i32 s45, s44, 31
	v_lshlrev_b32_e32 v138, 6, v150
	s_lshl_b64 s[44:45], s[44:45], 15
	v_and_or_b32 v138, v138, s62, v158
	s_add_u32 s44, s42, s44
	v_lshlrev_b32_e32 v138, 1, v138
	s_addc_u32 s45, s43, s45
	v_xor_b32_e32 v159, 32, v157
	s_or_b32 s51, s50, 2
	s_add_i32 s46, s46, s51
	s_ashr_i32 s47, s46, 31
	s_lshl_b64 s[46:47], s[46:47], 15
	s_add_u32 s46, s42, s46
	s_addc_u32 s47, s43, s47
	s_waitcnt vmcnt(0)
	v_pk_fma_f32 v[128:129], v[128:129], 0.5, v[162:163] op_sel_hi:[1,0,1]
	v_pk_fma_f32 v[170:171], v[126:127], 0.5, v[160:161] op_sel_hi:[1,0,1]
	v_pk_fma_f32 v[166:167], v[124:125], 0.5, v[166:167] op_sel_hi:[1,0,1]
	v_pk_fma_f32 v[164:165], v[122:123], 0.5, v[164:165] op_sel_hi:[1,0,1]
	v_cvt_pk_bf16_f32 v122, v170, v171
	v_cvt_pk_bf16_f32 v123, v128, v129
	v_cvt_pk_bf16_f32 v124, v164, v165
	v_cvt_pk_bf16_f32 v125, v166, v167
	global_store_dwordx4 v138, v[122:125], s[44:45]
	s_nop 1
	s_nop 0
	s_nop 1
	v_and_b32_e32 v123, 64, v157
	v_xor_b32_e32 v122, 16, v157
	v_add_u32_e32 v123, 64, v123
	v_cmp_lt_i32_e32 vcc, v122, v123
	v_mul_f32_e32 v129, v129, v129
	v_fmac_f32_e32 v129, v128, v128
	v_cndmask_b32_e32 v122, v157, v122, vcc
	v_cmp_lt_i32_e32 vcc, v159, v123
	v_lshlrev_b32_e32 v123, 2, v122
	v_mul_f32_e32 v165, v165, v165
	v_cndmask_b32_e32 v159, v157, v159, vcc
	v_lshlrev_b32_e32 v122, 2, v159
	v_mul_f32_e32 v159, v171, v171
	v_fmac_f32_e32 v159, v170, v170
	v_add_f32_e32 v128, v159, v129
	v_mul_f32_e32 v167, v167, v167
	v_fmac_f32_e32 v165, v164, v164
	v_fmac_f32_e32 v167, v166, v166
	v_add_f32_e32 v128, v165, v128
	v_add_f32_e32 v128, v167, v128
	s_waitcnt vmcnt(8)
	v_mov_b32_e32 v124, v172
	v_mov_b32_e32 v125, v173
	v_mov_b32_e32 v126, v174
	v_mov_b32_e32 v127, v175
	global_load_dwordx4 v[172:175], v[176:177], off offset:512
	v_pk_fma_f32 v[120:121], v[120:121], 0.5, v[126:127] op_sel_hi:[1,0,1]
	v_pk_fma_f32 v[118:119], v[118:119], 0.5, v[124:125] op_sel_hi:[1,0,1]
	s_waitcnt vmcnt(8)
	v_mov_b32_e32 v160, v180
	v_mov_b32_e32 v161, v181
	v_mov_b32_e32 v162, v182
	v_mov_b32_e32 v163, v183
	global_load_dwordx4 v[180:183], v[176:177], off offset:528
	v_pk_fma_f32 v[114:115], v[114:115], 0.5, v[160:161] op_sel_hi:[1,0,1]
	v_mul_f32_e32 v126, v119, v119
	v_mul_f32_e32 v127, v121, v121
	v_pk_fma_f32 v[124:125], v[116:117], 0.5, v[162:163] op_sel_hi:[1,0,1]
	v_mul_f32_e32 v129, v115, v115
	v_fmac_f32_e32 v126, v118, v118
	v_fmac_f32_e32 v127, v120, v120
	v_mul_f32_e32 v159, v125, v125
	v_cvt_pk_bf16_f32 v116, v118, v119
	v_fmac_f32_e32 v129, v114, v114
	v_add_f32_e32 v118, v126, v127
	v_fmac_f32_e32 v159, v124, v124
	v_add_f32_e32 v118, v129, v118
	v_add_f32_e32 v118, v159, v118
	v_cvt_pk_bf16_f32 v117, v120, v121
	v_add_f32_e32 v120, v128, v118
	v_cvt_pk_bf16_f32 v118, v114, v115
	ds_bpermute_b32 v114, v123, v120
	v_cvt_pk_bf16_f32 v119, v124, v125
	global_store_dwordx4 v138, v[116:119], s[46:47]
	s_waitcnt lgkmcnt(0)
	v_add_f32_e32 v114, v120, v114
	ds_bpermute_b32 v115, v122, v114
	s_and_saveexec_b64 s[48:49], s[0:1]
	s_cbranch_execz .LBB0_205
	v_lshl_add_u64 v[116:117], v[150:151], 2, s[10:11]
	s_waitcnt lgkmcnt(0)
	v_add_f32_e32 v114, v114, v115
	v_mov_b32_e32 v212, v116
	v_mov_b32_e32 v213, v117
	v_mov_b32_e32 v214, v114
; __host__ __device__ __forceinline__ size_t blk(int r, int k, int K) { return (((size_t)((r >> 8) * (K >> 6) + (k >> 6))) << 14) + (size_t)(((r & 255) << 6) + (k & 63)); }
; __device__ __forceinline__ float bflo(unsigned w) { return __uint_as_float(w << 16); }
; __device__ __forceinline__ float bfhi(unsigned w) { return __uint_as_float(w & 0xffff0000u); }
; __device__ __forceinline__ unsigned pk2(float lo, float hi) { f32x2 v = {lo, hi}; bf16x2_t b = __builtin_convertvector(v, bf16x2_t); return __builtin_bit_cast(unsigned, b); }
;     __device__ __forceinline__ void operator()(const f32x4 (&acc)[2][2][4][2], const Unit& u, int wr, int wc, int fr, int fq) const {
;     ...
;             for (int m = 0; m < 4; ++m) { const int row = row0 + ai * HALF + m * 16; const size_t off = (size_t)row * D + col0; float s = 0.f;
; #pragma unroll
;                 for (int bj = 0; bj < 2; ++bj) {
;                     f32x4 v0, v1;
;                     if (MODE == 0) { v0 = *(const f32x4*)(base + off + bj * HALF); v1 = *(const f32x4*)(base + off + bj * HALF + 4); }
;                     else { const u32x4 r = *(const u32x4*)(bb + blk(row, col0 + bj * HALF, D)); v0 = (f32x4){bflo(r.x), bfhi(r.x), bflo(r.y), bfhi(r.y)}; v1 = (f32x4){bflo(r.z), bfhi(r.z), bflo(r.w), bfhi(r.w)}; }
;                     v0 += acc[ai][bj][m][0] * alpha; v1 += acc[ai][bj][m][1] * alpha;
;                     if (MODE == 2) { *(f32x4*)(out + off + bj * HALF) = v0; *(f32x4*)(out + off + bj * HALF + 4) = v1; }
;                     else {
;                         s += (v0[0] * v0[0] + v0[1] * v0[1]) + (v0[2] * v0[2] + v0[3] * v0[3]) + (v1[0] * v1[0] + v1[1] * v1[1]) + (v1[2] * v1[2] + v1[3] * v1[3]);
;                         u32x4 w; w.x = pk2(v0[0], v0[1]); w.y = pk2(v0[2], v0[3]); w.z = pk2(v1[0], v1[1]); w.w = pk2(v1[2], v1[3]); *(u32x4*)(xb + blk(row, col0 + bj * HALF, D)) = w; } }
;                 if (MODE != 2) { s += __shfl_xor(s, 16); s += __shfl_xor(s, 32); if (fq == 0) unsafeAtomicAdd(ssq + row, s); } }
.LBB0_205:
	s_or_b64 exec, exec, s[48:49]
	v_or_b32_e32 v114, 16, v150
	s_waitcnt lgkmcnt(0)
	v_ashrrev_i32_e32 v115, 31, v114
	v_lshlrev_b64 v[116:117], 14, v[114:115]
	v_lshl_add_u64 v[116:117], s[8:9], 0, v[116:117]
	v_lshl_add_u64 v[120:121], v[148:149], 2, v[116:117]
	s_nop 1
	s_nop 1
	v_lshlrev_b32_e32 v128, 6, v114
	v_and_or_b32 v128, v128, s63, v158
	v_lshlrev_b32_e32 v128, 1, v128
	s_waitcnt vmcnt(9)
	v_mov_b32_e32 v116, v184
	v_mov_b32_e32 v117, v185
	v_mov_b32_e32 v118, v186
	v_mov_b32_e32 v119, v187
	v_lshl_add_u64 v[176:177], v[176:177], 0, s[98:99]
	global_load_dwordx4 v[184:187], v[176:177], off
	v_pk_fma_f32 v[118:119], v[112:113], 0.5, v[118:119] op_sel_hi:[1,0,1]
	v_pk_fma_f32 v[116:117], v[110:111], 0.5, v[116:117] op_sel_hi:[1,0,1]
	s_waitcnt vmcnt(9)
	v_mov_b32_e32 v124, v188
	v_mov_b32_e32 v125, v189
	v_mov_b32_e32 v126, v190
	v_mov_b32_e32 v127, v191
	global_load_dwordx4 v[188:191], v[176:177], off offset:16
	v_pk_fma_f32 v[126:127], v[108:109], 0.5, v[126:127] op_sel_hi:[1,0,1]
	v_pk_fma_f32 v[124:125], v[106:107], 0.5, v[124:125] op_sel_hi:[1,0,1]
	v_cvt_pk_bf16_f32 v106, v116, v117
	v_cvt_pk_bf16_f32 v107, v118, v119
	v_cvt_pk_bf16_f32 v108, v124, v125
	v_cvt_pk_bf16_f32 v109, v126, v127
	global_store_dwordx4 v128, v[106:109], s[44:45]
	s_nop 1
	s_nop 0
	s_nop 1
	v_mul_f32_e32 v117, v117, v117
	v_mul_f32_e32 v119, v119, v119
	v_mul_f32_e32 v120, v125, v125
	v_fmac_f32_e32 v117, v116, v116
	v_fmac_f32_e32 v119, v118, v118
	v_mul_f32_e32 v121, v127, v127
	v_fmac_f32_e32 v120, v124, v124
	v_add_f32_e32 v116, v117, v119
	v_fmac_f32_e32 v121, v126, v126
	v_add_f32_e32 v116, v120, v116
	v_add_f32_e32 v116, v121, v116
	s_waitcnt vmcnt(10)
	v_mov_b32_e32 v106, v196
	v_mov_b32_e32 v107, v197
	v_mov_b32_e32 v108, v198
	v_mov_b32_e32 v109, v199
	global_load_dwordx4 v[196:199], v[176:177], off offset:512
	v_pk_fma_f32 v[104:105], v[104:105], 0.5, v[108:109] op_sel_hi:[1,0,1]
	v_pk_fma_f32 v[102:103], v[102:103], 0.5, v[106:107] op_sel_hi:[1,0,1]
	s_waitcnt vmcnt(10)
	v_mov_b32_e32 v110, v200
	v_mov_b32_e32 v111, v201
	v_mov_b32_e32 v112, v202
	v_mov_b32_e32 v113, v203
	global_load_dwordx4 v[200:203], v[176:177], off offset:528
	v_pk_fma_f32 v[108:109], v[98:99], 0.5, v[110:111] op_sel_hi:[1,0,1]
	v_mul_f32_e32 v98, v103, v103
	v_mul_f32_e32 v99, v105, v105
	v_pk_fma_f32 v[106:107], v[100:101], 0.5, v[112:113] op_sel_hi:[1,0,1]
	v_mul_f32_e32 v100, v109, v109
	v_fmac_f32_e32 v98, v102, v102
	v_fmac_f32_e32 v99, v104, v104
	v_mul_f32_e32 v101, v107, v107
	v_fmac_f32_e32 v100, v108, v108
	v_add_f32_e32 v98, v98, v99
	v_add_f32_e32 v98, v100, v98
	v_fmac_f32_e32 v101, v106, v106
	v_add_f32_e32 v98, v101, v98
	v_add_f32_e32 v98, v116, v98
	ds_bpermute_b32 v99, v123, v98
	v_cvt_pk_bf16_f32 v100, v102, v103
	v_cvt_pk_bf16_f32 v101, v104, v105
	v_cvt_pk_bf16_f32 v102, v108, v109
	v_cvt_pk_bf16_f32 v103, v106, v107
	s_waitcnt lgkmcnt(0)
	v_add_f32_e32 v98, v98, v99
	ds_bpermute_b32 v99, v122, v98
	global_store_dwordx4 v128, v[100:103], s[46:47]
	s_and_saveexec_b64 s[48:49], s[0:1]
	s_cbranch_execz .LBB0_207
	v_lshl_add_u64 v[100:101], v[114:115], 2, s[10:11]
	s_waitcnt lgkmcnt(0)
	v_add_f32_e32 v98, v98, v99
	v_mov_b32_e32 v215, v98
.LBB0_207:
	s_or_b64 exec, exec, s[48:49]
	v_or_b32_e32 v98, 32, v150
	s_waitcnt lgkmcnt(0)
	v_ashrrev_i32_e32 v99, 31, v98
	v_lshlrev_b64 v[100:101], 14, v[98:99]
	v_lshl_add_u64 v[100:101], s[8:9], 0, v[100:101]
	v_lshl_add_u64 v[108:109], v[148:149], 2, v[100:101]
	s_nop 1
	s_nop 1
	v_lshlrev_b32_e32 v110, 6, v98
	v_and_or_b32 v110, v110, s64, v158
	v_lshlrev_b32_e32 v110, 1, v110
	s_waitcnt vmcnt(11)
	v_mov_b32_e32 v100, v204
	v_mov_b32_e32 v101, v205
	v_mov_b32_e32 v102, v206
	v_mov_b32_e32 v103, v207
	v_lshl_add_u64 v[176:177], v[176:177], 0, s[100:101]
	global_load_dwordx4 v[204:207], v[176:177], off
	v_pk_fma_f32 v[102:103], v[96:97], 0.5, v[102:103] op_sel_hi:[1,0,1]
	v_pk_fma_f32 v[100:101], v[94:95], 0.5, v[100:101] op_sel_hi:[1,0,1]
	s_waitcnt vmcnt(11)
	v_mov_b32_e32 v104, v208
	v_mov_b32_e32 v105, v209
	v_mov_b32_e32 v106, v210
	v_mov_b32_e32 v107, v211
	global_load_dwordx4 v[208:211], v[176:177], off offset:16
	v_pk_fma_f32 v[106:107], v[92:93], 0.5, v[106:107] op_sel_hi:[1,0,1]
	v_pk_fma_f32 v[104:105], v[90:91], 0.5, v[104:105] op_sel_hi:[1,0,1]
	v_cvt_pk_bf16_f32 v90, v100, v101
	v_cvt_pk_bf16_f32 v91, v102, v103
	v_cvt_pk_bf16_f32 v92, v104, v105
	v_cvt_pk_bf16_f32 v93, v106, v107
	global_store_dwordx4 v110, v[90:93], s[44:45]
	s_nop 1
	s_nop 0
	s_nop 1
	v_mul_f32_e32 v101, v101, v101
	v_mul_f32_e32 v103, v103, v103
	v_mul_f32_e32 v105, v105, v105
	v_fmac_f32_e32 v101, v100, v100
	v_fmac_f32_e32 v103, v102, v102
	v_mul_f32_e32 v107, v107, v107
	v_fmac_f32_e32 v105, v104, v104
	v_add_f32_e32 v100, v101, v103
	v_fmac_f32_e32 v107, v106, v106
	v_add_f32_e32 v100, v105, v100
	v_add_f32_e32 v100, v107, v100
	s_waitcnt vmcnt(11)
	v_mov_b32_e32 v90, v172
	v_mov_b32_e32 v91, v173
	v_mov_b32_e32 v92, v174
	v_mov_b32_e32 v93, v175
	global_load_dwordx4 v[172:175], v[176:177], off offset:512
	v_pk_fma_f32 v[88:89], v[88:89], 0.5, v[92:93] op_sel_hi:[1,0,1]
	v_pk_fma_f32 v[86:87], v[86:87], 0.5, v[90:91] op_sel_hi:[1,0,1]
	s_waitcnt vmcnt(11)
	v_mov_b32_e32 v94, v180
	v_mov_b32_e32 v95, v181
	v_mov_b32_e32 v96, v182
	v_mov_b32_e32 v97, v183
	global_load_dwordx4 v[180:183], v[176:177], off offset:528
	v_pk_fma_f32 v[92:93], v[82:83], 0.5, v[94:95] op_sel_hi:[1,0,1]
	v_mul_f32_e32 v82, v87, v87
	v_mul_f32_e32 v83, v89, v89
	v_pk_fma_f32 v[90:91], v[84:85], 0.5, v[96:97] op_sel_hi:[1,0,1]
	v_mul_f32_e32 v84, v93, v93
	v_fmac_f32_e32 v82, v86, v86
	v_fmac_f32_e32 v83, v88, v88
	v_mul_f32_e32 v85, v91, v91
	v_fmac_f32_e32 v84, v92, v92
	v_add_f32_e32 v82, v82, v83
	v_add_f32_e32 v82, v84, v82
	v_fmac_f32_e32 v85, v90, v90
	v_add_f32_e32 v82, v85, v82
	v_add_f32_e32 v82, v100, v82
	ds_bpermute_b32 v83, v123, v82
	v_cvt_pk_bf16_f32 v84, v86, v87
	v_cvt_pk_bf16_f32 v85, v88, v89
	v_cvt_pk_bf16_f32 v86, v92, v93
	v_cvt_pk_bf16_f32 v87, v90, v91
	s_waitcnt lgkmcnt(0)
	v_add_f32_e32 v82, v82, v83
	ds_bpermute_b32 v83, v122, v82
	global_store_dwordx4 v110, v[84:87], s[46:47]
	s_and_saveexec_b64 s[48:49], s[0:1]
	s_cbranch_execz .LBB0_209
	v_lshl_add_u64 v[84:85], v[98:99], 2, s[10:11]
	s_waitcnt lgkmcnt(0)
	v_add_f32_e32 v82, v82, v83
	v_mov_b32_e32 v216, v82
; __host__ __device__ __forceinline__ size_t blk(int r, int k, int K) { return (((size_t)((r >> 8) * (K >> 6) + (k >> 6))) << 14) + (size_t)(((r & 255) << 6) + (k & 63)); }
; __device__ __forceinline__ float bflo(unsigned w) { return __uint_as_float(w << 16); }
; __device__ __forceinline__ float bfhi(unsigned w) { return __uint_as_float(w & 0xffff0000u); }
; __device__ __forceinline__ unsigned pk2(float lo, float hi) { f32x2 v = {lo, hi}; bf16x2_t b = __builtin_convertvector(v, bf16x2_t); return __builtin_bit_cast(unsigned, b); }
;     __device__ __forceinline__ void operator()(const f32x4 (&acc)[2][2][4][2], const Unit& u, int wr, int wc, int fr, int fq) const {
;     ...
;             for (int m = 0; m < 4; ++m) { const int row = row0 + ai * HALF + m * 16; const size_t off = (size_t)row * D + col0; float s = 0.f;
; #pragma unroll
;                 for (int bj = 0; bj < 2; ++bj) {
;                     f32x4 v0, v1;
;                     if (MODE == 0) { v0 = *(const f32x4*)(base + off + bj * HALF); v1 = *(const f32x4*)(base + off + bj * HALF + 4); }
;                     else { const u32x4 r = *(const u32x4*)(bb + blk(row, col0 + bj * HALF, D)); v0 = (f32x4){bflo(r.x), bfhi(r.x), bflo(r.y), bfhi(r.y)}; v1 = (f32x4){bflo(r.z), bfhi(r.z), bflo(r.w), bfhi(r.w)}; }
;                     v0 += acc[ai][bj][m][0] * alpha; v1 += acc[ai][bj][m][1] * alpha;
;                     if (MODE == 2) { *(f32x4*)(out + off + bj * HALF) = v0; *(f32x4*)(out + off + bj * HALF + 4) = v1; }
;                     else {
;                         s += (v0[0] * v0[0] + v0[1] * v0[1]) + (v0[2] * v0[2] + v0[3] * v0[3]) + (v1[0] * v1[0] + v1[1] * v1[1]) + (v1[2] * v1[2] + v1[3] * v1[3]);
;                         u32x4 w; w.x = pk2(v0[0], v0[1]); w.y = pk2(v0[2], v0[3]); w.z = pk2(v1[0], v1[1]); w.w = pk2(v1[2], v1[3]); *(u32x4*)(xb + blk(row, col0 + bj * HALF, D)) = w; } }
;                 if (MODE != 2) { s += __shfl_xor(s, 16); s += __shfl_xor(s, 32); if (fq == 0) unsafeAtomicAdd(ssq + row, s); } }
.LBB0_209:
	s_or_b64 exec, exec, s[48:49]
	v_or_b32_e32 v82, 48, v150
	s_waitcnt lgkmcnt(0)
	v_ashrrev_i32_e32 v83, 31, v82
	v_lshlrev_b64 v[84:85], 14, v[82:83]
	v_lshl_add_u64 v[84:85], s[8:9], 0, v[84:85]
	v_lshl_add_u64 v[92:93], v[148:149], 2, v[84:85]
	s_nop 1
	s_nop 1
	v_lshlrev_b32_e32 v94, 6, v82
	v_and_or_b32 v94, v94, s65, v158
	v_lshlrev_b32_e32 v94, 1, v94
	s_waitcnt vmcnt(11)
	v_mov_b32_e32 v84, v184
	v_mov_b32_e32 v85, v185
	v_mov_b32_e32 v86, v186
	v_mov_b32_e32 v87, v187
	v_lshl_add_u64 v[176:177], v[176:177], 0, s[98:99]
	global_load_dwordx4 v[184:187], v[176:177], off
	v_pk_fma_f32 v[86:87], v[80:81], 0.5, v[86:87] op_sel_hi:[1,0,1]
	v_pk_fma_f32 v[84:85], v[78:79], 0.5, v[84:85] op_sel_hi:[1,0,1]
	s_waitcnt vmcnt(11)
	v_mov_b32_e32 v88, v188
	v_mov_b32_e32 v89, v189
	v_mov_b32_e32 v90, v190
	v_mov_b32_e32 v91, v191
	global_load_dwordx4 v[188:191], v[176:177], off offset:16
	v_pk_fma_f32 v[90:91], v[76:77], 0.5, v[90:91] op_sel_hi:[1,0,1]
	v_pk_fma_f32 v[88:89], v[74:75], 0.5, v[88:89] op_sel_hi:[1,0,1]
	v_cvt_pk_bf16_f32 v74, v84, v85
	v_cvt_pk_bf16_f32 v75, v86, v87
	v_cvt_pk_bf16_f32 v76, v88, v89
	v_cvt_pk_bf16_f32 v77, v90, v91
	global_store_dwordx4 v94, v[74:77], s[44:45]
	s_nop 1
	s_nop 0
	s_nop 1
	v_mul_f32_e32 v85, v85, v85
	v_mul_f32_e32 v87, v87, v87
	v_mul_f32_e32 v89, v89, v89
	v_fmac_f32_e32 v85, v84, v84
	v_fmac_f32_e32 v87, v86, v86
	v_mul_f32_e32 v91, v91, v91
	v_fmac_f32_e32 v89, v88, v88
	v_add_f32_e32 v84, v85, v87
	v_fmac_f32_e32 v91, v90, v90
	v_add_f32_e32 v84, v89, v84
	v_add_f32_e32 v84, v91, v84
	s_waitcnt vmcnt(11)
	v_mov_b32_e32 v74, v196
	v_mov_b32_e32 v75, v197
	v_mov_b32_e32 v76, v198
	v_mov_b32_e32 v77, v199
	global_load_dwordx4 v[196:199], v[176:177], off offset:512
	v_pk_fma_f32 v[72:73], v[72:73], 0.5, v[76:77] op_sel_hi:[1,0,1]
	v_pk_fma_f32 v[70:71], v[70:71], 0.5, v[74:75] op_sel_hi:[1,0,1]
	s_waitcnt vmcnt(11)
	v_mov_b32_e32 v78, v200
	v_mov_b32_e32 v79, v201
	v_mov_b32_e32 v80, v202
	v_mov_b32_e32 v81, v203
	global_load_dwordx4 v[200:203], v[176:177], off offset:528
	v_pk_fma_f32 v[76:77], v[66:67], 0.5, v[78:79] op_sel_hi:[1,0,1]
	v_mul_f32_e32 v66, v71, v71
	v_mul_f32_e32 v67, v73, v73
	v_pk_fma_f32 v[74:75], v[68:69], 0.5, v[80:81] op_sel_hi:[1,0,1]
	v_mul_f32_e32 v68, v77, v77
	v_fmac_f32_e32 v66, v70, v70
	v_fmac_f32_e32 v67, v72, v72
	v_mul_f32_e32 v69, v75, v75
	v_fmac_f32_e32 v68, v76, v76
	v_add_f32_e32 v66, v66, v67
	v_add_f32_e32 v66, v68, v66
	v_fmac_f32_e32 v69, v74, v74
	v_add_f32_e32 v66, v69, v66
	v_add_f32_e32 v66, v84, v66
	ds_bpermute_b32 v67, v123, v66
	v_cvt_pk_bf16_f32 v68, v70, v71
	v_cvt_pk_bf16_f32 v69, v72, v73
	v_cvt_pk_bf16_f32 v70, v76, v77
	v_cvt_pk_bf16_f32 v71, v74, v75
	s_waitcnt lgkmcnt(0)
	v_add_f32_e32 v66, v66, v67
	ds_bpermute_b32 v67, v122, v66
	global_store_dwordx4 v94, v[68:71], s[46:47]
	s_and_saveexec_b64 s[44:45], s[0:1]
	s_cbranch_execz .LBB0_211
	v_lshl_add_u64 v[68:69], v[82:83], 2, s[10:11]
	s_waitcnt lgkmcnt(0)
	v_add_f32_e32 v66, v66, v67
	v_mov_b32_e32 v217, v66
.LBB0_211:
	s_or_b64 exec, exec, s[44:45]
	v_add_u32_e32 v68, 0x80, v150
	v_ashrrev_i32_e32 v69, 31, v68
	s_waitcnt lgkmcnt(0)
	v_lshlrev_b64 v[66:67], 14, v[68:69]
	v_lshl_add_u64 v[66:67], s[8:9], 0, v[66:67]
	v_lshl_add_u64 v[78:79], v[148:149], 2, v[66:67]
	s_nop 1
	s_nop 1
	v_ashrrev_i32_e32 v66, 2, v68
	v_lshlrev_b32_e32 v67, 6, v68
	v_and_b32_e32 v82, 0xffffffc0, v66
	v_and_or_b32 v67, v67, s62, v158
	v_add_u32_e32 v66, s50, v82
	v_lshlrev_b32_e32 v138, 1, v67
	v_ashrrev_i32_e32 v67, 31, v66
	v_lshlrev_b64 v[66:67], 15, v[66:67]
	v_lshl_add_u64 v[66:67], s[42:43], 0, v[66:67]
	v_lshl_add_u64 v[80:81], v[66:67], 0, v[138:139]
	s_waitcnt vmcnt(11)
	v_mov_b32_e32 v70, v204
	v_mov_b32_e32 v71, v205
	v_mov_b32_e32 v72, v206
	v_mov_b32_e32 v73, v207
	v_lshl_add_u64 v[176:177], v[176:177], 0, s[98:99]
	global_load_dwordx4 v[204:207], v[176:177], off
	v_pk_fma_f32 v[72:73], v[64:65], 0.5, v[72:73] op_sel_hi:[1,0,1]
	v_pk_fma_f32 v[70:71], v[62:63], 0.5, v[70:71] op_sel_hi:[1,0,1]
	s_waitcnt vmcnt(11)
	v_mov_b32_e32 v74, v208
	v_mov_b32_e32 v75, v209
	v_mov_b32_e32 v76, v210
	v_mov_b32_e32 v77, v211
	global_load_dwordx4 v[208:211], v[176:177], off offset:16
	v_pk_fma_f32 v[76:77], v[60:61], 0.5, v[76:77] op_sel_hi:[1,0,1]
	v_pk_fma_f32 v[74:75], v[58:59], 0.5, v[74:75] op_sel_hi:[1,0,1]
	v_cvt_pk_bf16_f32 v58, v70, v71
	v_cvt_pk_bf16_f32 v59, v72, v73
	v_cvt_pk_bf16_f32 v60, v74, v75
	v_cvt_pk_bf16_f32 v61, v76, v77
	global_store_dwordx4 v[80:81], v[58:61], off
	s_nop 1
	s_nop 0
	s_nop 1
	v_mul_f32_e32 v71, v71, v71
	v_mul_f32_e32 v73, v73, v73
	v_mul_f32_e32 v75, v75, v75
	v_fmac_f32_e32 v71, v70, v70
	v_fmac_f32_e32 v73, v72, v72
	v_mul_f32_e32 v77, v77, v77
	v_fmac_f32_e32 v75, v74, v74
	v_add_f32_e32 v70, v71, v73
	v_fmac_f32_e32 v77, v76, v76
	v_add_f32_e32 v70, v75, v70
	v_add_f32_e32 v70, v77, v70
	s_waitcnt vmcnt(11)
	v_mov_b32_e32 v58, v172
	v_mov_b32_e32 v59, v173
	v_mov_b32_e32 v60, v174
	v_mov_b32_e32 v61, v175
	global_load_dwordx4 v[172:175], v[176:177], off offset:512
	v_pk_fma_f32 v[56:57], v[56:57], 0.5, v[60:61] op_sel_hi:[1,0,1]
	v_pk_fma_f32 v[58:59], v[54:55], 0.5, v[58:59] op_sel_hi:[1,0,1]
	s_waitcnt vmcnt(11)
	v_mov_b32_e32 v62, v180
	v_mov_b32_e32 v63, v181
	v_mov_b32_e32 v64, v182
	v_mov_b32_e32 v65, v183
	global_load_dwordx4 v[180:183], v[176:177], off offset:528
	v_pk_fma_f32 v[50:51], v[50:51], 0.5, v[62:63] op_sel_hi:[1,0,1]
	v_mul_f32_e32 v55, v59, v59
	v_mul_f32_e32 v60, v57, v57
	v_pk_fma_f32 v[52:53], v[52:53], 0.5, v[64:65] op_sel_hi:[1,0,1]
	v_mul_f32_e32 v61, v51, v51
	v_fmac_f32_e32 v55, v58, v58
	v_fmac_f32_e32 v60, v56, v56
	v_mul_f32_e32 v62, v53, v53
	v_fmac_f32_e32 v61, v50, v50
	v_add_f32_e32 v55, v55, v60
	v_fmac_f32_e32 v62, v52, v52
	v_add_f32_e32 v55, v61, v55
	v_add_f32_e32 v55, v62, v55
	v_cvt_pk_bf16_f32 v54, v58, v59
	v_add_f32_e32 v58, v70, v55
	ds_bpermute_b32 v59, v123, v58
	v_cvt_pk_bf16_f32 v55, v56, v57
	v_cvt_pk_bf16_f32 v57, v52, v53
	v_cvt_pk_bf16_f32 v56, v50, v51
	v_add_u32_e32 v50, s51, v82
	s_waitcnt lgkmcnt(0)
	v_add_f32_e32 v52, v58, v59
	ds_bpermute_b32 v53, v122, v52
	v_ashrrev_i32_e32 v51, 31, v50
	v_lshlrev_b64 v[50:51], 15, v[50:51]
	v_lshl_add_u64 v[50:51], s[42:43], 0, v[50:51]
	v_lshl_add_u64 v[58:59], v[50:51], 0, v[138:139]
	global_store_dwordx4 v[58:59], v[54:57], off
	s_and_saveexec_b64 s[44:45], s[0:1]
	s_cbranch_execz .LBB0_213
	v_lshl_add_u64 v[54:55], v[68:69], 2, s[10:11]
	s_waitcnt lgkmcnt(0)
	v_add_f32_e32 v52, v52, v53
	v_mov_b32_e32 v218, v52
; __host__ __device__ __forceinline__ size_t blk(int r, int k, int K) { return (((size_t)((r >> 8) * (K >> 6) + (k >> 6))) << 14) + (size_t)(((r & 255) << 6) + (k & 63)); }
; __device__ __forceinline__ float bflo(unsigned w) { return __uint_as_float(w << 16); }
; __device__ __forceinline__ float bfhi(unsigned w) { return __uint_as_float(w & 0xffff0000u); }
; __device__ __forceinline__ unsigned pk2(float lo, float hi) { f32x2 v = {lo, hi}; bf16x2_t b = __builtin_convertvector(v, bf16x2_t); return __builtin_bit_cast(unsigned, b); }
;     __device__ __forceinline__ void operator()(const f32x4 (&acc)[2][2][4][2], const Unit& u, int wr, int wc, int fr, int fq) const {
;     ...
;             for (int m = 0; m < 4; ++m) { const int row = row0 + ai * HALF + m * 16; const size_t off = (size_t)row * D + col0; float s = 0.f;
; #pragma unroll
;                 for (int bj = 0; bj < 2; ++bj) {
;                     f32x4 v0, v1;
;                     if (MODE == 0) { v0 = *(const f32x4*)(base + off + bj * HALF); v1 = *(const f32x4*)(base + off + bj * HALF + 4); }
;                     else { const u32x4 r = *(const u32x4*)(bb + blk(row, col0 + bj * HALF, D)); v0 = (f32x4){bflo(r.x), bfhi(r.x), bflo(r.y), bfhi(r.y)}; v1 = (f32x4){bflo(r.z), bfhi(r.z), bflo(r.w), bfhi(r.w)}; }
;                     v0 += acc[ai][bj][m][0] * alpha; v1 += acc[ai][bj][m][1] * alpha;
;                     if (MODE == 2) { *(f32x4*)(out + off + bj * HALF) = v0; *(f32x4*)(out + off + bj * HALF + 4) = v1; }
;                     else {
;                         s += (v0[0] * v0[0] + v0[1] * v0[1]) + (v0[2] * v0[2] + v0[3] * v0[3]) + (v1[0] * v1[0] + v1[1] * v1[1]) + (v1[2] * v1[2] + v1[3] * v1[3]);
;                         u32x4 w; w.x = pk2(v0[0], v0[1]); w.y = pk2(v0[2], v0[3]); w.z = pk2(v1[0], v1[1]); w.w = pk2(v1[2], v1[3]); *(u32x4*)(xb + blk(row, col0 + bj * HALF, D)) = w; } }
;                 if (MODE != 2) { s += __shfl_xor(s, 16); s += __shfl_xor(s, 32); if (fq == 0) unsafeAtomicAdd(ssq + row, s); } }
.LBB0_213:
	s_or_b64 exec, exec, s[44:45]
	v_add_u32_e32 v52, 0x90, v150
	s_waitcnt lgkmcnt(0)
	v_ashrrev_i32_e32 v53, 31, v52
	v_lshlrev_b64 v[54:55], 14, v[52:53]
	v_lshl_add_u64 v[54:55], s[8:9], 0, v[54:55]
	v_lshl_add_u64 v[62:63], v[148:149], 2, v[54:55]
	s_nop 1
	s_nop 1
	v_lshlrev_b32_e32 v64, 6, v52
	v_and_or_b32 v64, v64, s63, v158
	v_lshlrev_b32_e32 v138, 1, v64
	v_lshl_add_u64 v[64:65], v[66:67], 0, v[138:139]
	s_waitcnt vmcnt(11)
	v_mov_b32_e32 v54, v184
	v_mov_b32_e32 v55, v185
	v_mov_b32_e32 v56, v186
	v_mov_b32_e32 v57, v187
	v_lshl_add_u64 v[176:177], v[176:177], 0, s[98:99]
	global_load_dwordx4 v[184:187], v[176:177], off
	v_pk_fma_f32 v[56:57], v[48:49], 0.5, v[56:57] op_sel_hi:[1,0,1]
	v_pk_fma_f32 v[54:55], v[46:47], 0.5, v[54:55] op_sel_hi:[1,0,1]
	s_waitcnt vmcnt(11)
	v_mov_b32_e32 v58, v188
	v_mov_b32_e32 v59, v189
	v_mov_b32_e32 v60, v190
	v_mov_b32_e32 v61, v191
	global_load_dwordx4 v[188:191], v[176:177], off offset:16
	v_pk_fma_f32 v[60:61], v[44:45], 0.5, v[60:61] op_sel_hi:[1,0,1]
	v_pk_fma_f32 v[58:59], v[42:43], 0.5, v[58:59] op_sel_hi:[1,0,1]
	v_cvt_pk_bf16_f32 v42, v54, v55
	v_cvt_pk_bf16_f32 v43, v56, v57
	v_cvt_pk_bf16_f32 v44, v58, v59
	v_cvt_pk_bf16_f32 v45, v60, v61
	global_store_dwordx4 v[64:65], v[42:45], off
	s_nop 1
	s_nop 0
	s_nop 1
	v_mul_f32_e32 v55, v55, v55
	v_mul_f32_e32 v57, v57, v57
	v_mul_f32_e32 v59, v59, v59
	v_fmac_f32_e32 v55, v54, v54
	v_fmac_f32_e32 v57, v56, v56
	v_mul_f32_e32 v61, v61, v61
	v_fmac_f32_e32 v59, v58, v58
	v_add_f32_e32 v54, v55, v57
	v_fmac_f32_e32 v61, v60, v60
	v_add_f32_e32 v54, v59, v54
	v_add_f32_e32 v54, v61, v54
	s_waitcnt vmcnt(11)
	v_mov_b32_e32 v42, v196
	v_mov_b32_e32 v43, v197
	v_mov_b32_e32 v44, v198
	v_mov_b32_e32 v45, v199
	global_load_dwordx4 v[196:199], v[176:177], off offset:512
	v_pk_fma_f32 v[40:41], v[40:41], 0.5, v[44:45] op_sel_hi:[1,0,1]
	v_pk_fma_f32 v[38:39], v[38:39], 0.5, v[42:43] op_sel_hi:[1,0,1]
	s_waitcnt vmcnt(11)
	v_mov_b32_e32 v46, v200
	v_mov_b32_e32 v47, v201
	v_mov_b32_e32 v48, v202
	v_mov_b32_e32 v49, v203
	global_load_dwordx4 v[200:203], v[176:177], off offset:528
	v_pk_fma_f32 v[44:45], v[34:35], 0.5, v[46:47] op_sel_hi:[1,0,1]
	v_mul_f32_e32 v34, v39, v39
	v_mul_f32_e32 v35, v41, v41
	v_pk_fma_f32 v[42:43], v[36:37], 0.5, v[48:49] op_sel_hi:[1,0,1]
	v_mul_f32_e32 v36, v45, v45
	v_fmac_f32_e32 v34, v38, v38
	v_fmac_f32_e32 v35, v40, v40
	v_mul_f32_e32 v37, v43, v43
	v_fmac_f32_e32 v36, v44, v44
	v_add_f32_e32 v34, v34, v35
	v_add_f32_e32 v34, v36, v34
	v_fmac_f32_e32 v37, v42, v42
	v_add_f32_e32 v34, v37, v34
	v_add_f32_e32 v34, v54, v34
	ds_bpermute_b32 v35, v123, v34
	v_cvt_pk_bf16_f32 v36, v38, v39
	v_cvt_pk_bf16_f32 v37, v40, v41
	v_cvt_pk_bf16_f32 v38, v44, v45
	v_cvt_pk_bf16_f32 v39, v42, v43
	s_waitcnt lgkmcnt(0)
	v_add_f32_e32 v34, v34, v35
	ds_bpermute_b32 v35, v122, v34
	v_lshl_add_u64 v[40:41], v[50:51], 0, v[138:139]
	global_store_dwordx4 v[40:41], v[36:39], off
	s_and_saveexec_b64 s[44:45], s[0:1]
	s_cbranch_execz .LBB0_215
	v_lshl_add_u64 v[36:37], v[52:53], 2, s[10:11]
	s_waitcnt lgkmcnt(0)
	v_add_f32_e32 v34, v34, v35
	v_mov_b32_e32 v219, v34
.LBB0_215:
	s_or_b64 exec, exec, s[44:45]
	v_add_u32_e32 v34, 0xa0, v150
	s_waitcnt lgkmcnt(0)
	v_ashrrev_i32_e32 v35, 31, v34
	v_lshlrev_b64 v[36:37], 14, v[34:35]
	v_lshl_add_u64 v[36:37], s[8:9], 0, v[36:37]
	v_lshl_add_u64 v[44:45], v[148:149], 2, v[36:37]
	s_nop 1
	s_nop 1
	v_lshlrev_b32_e32 v46, 6, v34
	v_and_or_b32 v46, v46, s64, v158
	v_lshlrev_b32_e32 v138, 1, v46
	v_lshl_add_u64 v[46:47], v[66:67], 0, v[138:139]
	s_waitcnt vmcnt(11)
	v_mov_b32_e32 v36, v204
	v_mov_b32_e32 v37, v205
	v_mov_b32_e32 v38, v206
	v_mov_b32_e32 v39, v207
	v_pk_fma_f32 v[38:39], v[32:33], 0.5, v[38:39] op_sel_hi:[1,0,1]
	v_pk_fma_f32 v[36:37], v[30:31], 0.5, v[36:37] op_sel_hi:[1,0,1]
	s_waitcnt vmcnt(10)
	v_mov_b32_e32 v40, v208
	v_mov_b32_e32 v41, v209
	v_mov_b32_e32 v42, v210
	v_mov_b32_e32 v43, v211
	v_pk_fma_f32 v[42:43], v[28:29], 0.5, v[42:43] op_sel_hi:[1,0,1]
	v_pk_fma_f32 v[40:41], v[26:27], 0.5, v[40:41] op_sel_hi:[1,0,1]
	v_cvt_pk_bf16_f32 v26, v36, v37
	v_cvt_pk_bf16_f32 v27, v38, v39
	v_cvt_pk_bf16_f32 v28, v40, v41
	v_cvt_pk_bf16_f32 v29, v42, v43
	global_store_dwordx4 v[46:47], v[26:29], off
	s_nop 1
	s_nop 0
	s_nop 1
	v_mul_f32_e32 v37, v37, v37
	v_mul_f32_e32 v39, v39, v39
	v_mul_f32_e32 v41, v41, v41
	v_fmac_f32_e32 v37, v36, v36
	v_fmac_f32_e32 v39, v38, v38
	v_mul_f32_e32 v43, v43, v43
	v_fmac_f32_e32 v41, v40, v40
	v_add_f32_e32 v36, v37, v39
	v_fmac_f32_e32 v43, v42, v42
	v_add_f32_e32 v36, v41, v36
	v_add_f32_e32 v36, v43, v36
	s_waitcnt vmcnt(9)
	v_mov_b32_e32 v26, v172
	v_mov_b32_e32 v27, v173
	v_mov_b32_e32 v28, v174
	v_mov_b32_e32 v29, v175
	v_pk_fma_f32 v[24:25], v[24:25], 0.5, v[28:29] op_sel_hi:[1,0,1]
	v_pk_fma_f32 v[22:23], v[22:23], 0.5, v[26:27] op_sel_hi:[1,0,1]
	s_waitcnt vmcnt(8)
	v_mov_b32_e32 v30, v180
	v_mov_b32_e32 v31, v181
	v_mov_b32_e32 v32, v182
	v_mov_b32_e32 v33, v183
	v_pk_fma_f32 v[28:29], v[18:19], 0.5, v[30:31] op_sel_hi:[1,0,1]
	v_mul_f32_e32 v18, v23, v23
	v_mul_f32_e32 v19, v25, v25
	v_pk_fma_f32 v[26:27], v[20:21], 0.5, v[32:33] op_sel_hi:[1,0,1]
	v_mul_f32_e32 v20, v29, v29
	v_fmac_f32_e32 v18, v22, v22
	v_fmac_f32_e32 v19, v24, v24
	v_mul_f32_e32 v21, v27, v27
	v_fmac_f32_e32 v20, v28, v28
	v_add_f32_e32 v18, v18, v19
	v_add_f32_e32 v18, v20, v18
	v_fmac_f32_e32 v21, v26, v26
	v_add_f32_e32 v18, v21, v18
	v_add_f32_e32 v18, v36, v18
	ds_bpermute_b32 v19, v123, v18
	v_cvt_pk_bf16_f32 v20, v22, v23
	v_cvt_pk_bf16_f32 v21, v24, v25
	v_cvt_pk_bf16_f32 v22, v28, v29
	v_cvt_pk_bf16_f32 v23, v26, v27
	s_waitcnt lgkmcnt(0)
	v_add_f32_e32 v18, v18, v19
	ds_bpermute_b32 v19, v122, v18
	v_lshl_add_u64 v[24:25], v[50:51], 0, v[138:139]
	global_store_dwordx4 v[24:25], v[20:23], off
	s_and_saveexec_b64 s[44:45], s[0:1]
	s_cbranch_execz .LBB0_217
	v_lshl_add_u64 v[20:21], v[34:35], 2, s[10:11]
	s_waitcnt lgkmcnt(0)
	v_add_f32_e32 v18, v18, v19
	v_mov_b32_e32 v220, v18
; __host__ __device__ __forceinline__ size_t blk(int r, int k, int K) { return (((size_t)((r >> 8) * (K >> 6) + (k >> 6))) << 14) + (size_t)(((r & 255) << 6) + (k & 63)); }
; __device__ __forceinline__ float bflo(unsigned w) { return __uint_as_float(w << 16); }
; __device__ __forceinline__ float bfhi(unsigned w) { return __uint_as_float(w & 0xffff0000u); }
; __device__ __forceinline__ unsigned pk2(float lo, float hi) { f32x2 v = {lo, hi}; bf16x2_t b = __builtin_convertvector(v, bf16x2_t); return __builtin_bit_cast(unsigned, b); }
;     __device__ __forceinline__ void operator()(const f32x4 (&acc)[2][2][4][2], const Unit& u, int wr, int wc, int fr, int fq) const {
;     ...
;             for (int m = 0; m < 4; ++m) { const int row = row0 + ai * HALF + m * 16; const size_t off = (size_t)row * D + col0; float s = 0.f;
; #pragma unroll
;                 for (int bj = 0; bj < 2; ++bj) {
;                     f32x4 v0, v1;
;                     if (MODE == 0) { v0 = *(const f32x4*)(base + off + bj * HALF); v1 = *(const f32x4*)(base + off + bj * HALF + 4); }
;                     else { const u32x4 r = *(const u32x4*)(bb + blk(row, col0 + bj * HALF, D)); v0 = (f32x4){bflo(r.x), bfhi(r.x), bflo(r.y), bfhi(r.y)}; v1 = (f32x4){bflo(r.z), bfhi(r.z), bflo(r.w), bfhi(r.w)}; }
;                     v0 += acc[ai][bj][m][0] * alpha; v1 += acc[ai][bj][m][1] * alpha;
;                     if (MODE == 2) { *(f32x4*)(out + off + bj * HALF) = v0; *(f32x4*)(out + off + bj * HALF + 4) = v1; }
;                     else {
;                         s += (v0[0] * v0[0] + v0[1] * v0[1]) + (v0[2] * v0[2] + v0[3] * v0[3]) + (v1[0] * v1[0] + v1[1] * v1[1]) + (v1[2] * v1[2] + v1[3] * v1[3]);
;                         u32x4 w; w.x = pk2(v0[0], v0[1]); w.y = pk2(v0[2], v0[3]); w.z = pk2(v1[0], v1[1]); w.w = pk2(v1[2], v1[3]); *(u32x4*)(xb + blk(row, col0 + bj * HALF, D)) = w; } }
;                 if (MODE != 2) { s += __shfl_xor(s, 16); s += __shfl_xor(s, 32); if (fq == 0) unsafeAtomicAdd(ssq + row, s); } }
.LBB0_217:
	s_or_b64 exec, exec, s[44:45]
	v_add_u32_e32 v18, 0xb0, v150
	s_waitcnt lgkmcnt(0)
	v_ashrrev_i32_e32 v19, 31, v18
	v_lshlrev_b64 v[20:21], 14, v[18:19]
	v_lshl_add_u64 v[20:21], s[8:9], 0, v[20:21]
	v_lshl_add_u64 v[28:29], v[148:149], 2, v[20:21]
	s_nop 1
	s_nop 1
	v_lshlrev_b32_e32 v30, 6, v18
	v_and_or_b32 v30, v30, s65, v158
	v_lshlrev_b32_e32 v138, 1, v30
	v_lshl_add_u64 v[30:31], v[66:67], 0, v[138:139]
	s_waitcnt vmcnt(7)
	v_mov_b32_e32 v20, v184
	v_mov_b32_e32 v21, v185
	v_mov_b32_e32 v22, v186
	v_mov_b32_e32 v23, v187
	v_pk_fma_f32 v[22:23], v[16:17], 0.5, v[22:23] op_sel_hi:[1,0,1]
	v_pk_fma_f32 v[20:21], v[14:15], 0.5, v[20:21] op_sel_hi:[1,0,1]
	s_waitcnt vmcnt(6)
	v_mov_b32_e32 v24, v188
	v_mov_b32_e32 v25, v189
	v_mov_b32_e32 v26, v190
	v_mov_b32_e32 v27, v191
	v_pk_fma_f32 v[26:27], v[12:13], 0.5, v[26:27] op_sel_hi:[1,0,1]
	v_pk_fma_f32 v[24:25], v[10:11], 0.5, v[24:25] op_sel_hi:[1,0,1]
	v_cvt_pk_bf16_f32 v10, v20, v21
	v_cvt_pk_bf16_f32 v11, v22, v23
	v_cvt_pk_bf16_f32 v12, v24, v25
	v_cvt_pk_bf16_f32 v13, v26, v27
	global_store_dwordx4 v[30:31], v[10:13], off
	s_nop 1
	s_nop 0
	s_nop 1
	v_mul_f32_e32 v21, v21, v21
	v_mul_f32_e32 v23, v23, v23
	v_mul_f32_e32 v25, v25, v25
	v_fmac_f32_e32 v21, v20, v20
	v_fmac_f32_e32 v23, v22, v22
	v_mul_f32_e32 v27, v27, v27
	v_fmac_f32_e32 v25, v24, v24
	v_add_f32_e32 v20, v21, v23
	v_fmac_f32_e32 v27, v26, v26
	v_add_f32_e32 v20, v25, v20
	v_add_f32_e32 v20, v27, v20
	s_waitcnt vmcnt(5)
	v_mov_b32_e32 v10, v196
	v_mov_b32_e32 v11, v197
	v_mov_b32_e32 v12, v198
	v_mov_b32_e32 v13, v199
	v_pk_fma_f32 v[8:9], v[8:9], 0.5, v[12:13] op_sel_hi:[1,0,1]
	v_pk_fma_f32 v[6:7], v[6:7], 0.5, v[10:11] op_sel_hi:[1,0,1]
	s_waitcnt vmcnt(4)
	v_mov_b32_e32 v14, v200
	v_mov_b32_e32 v15, v201
	v_mov_b32_e32 v16, v202
	v_mov_b32_e32 v17, v203
	v_pk_fma_f32 v[12:13], v[2:3], 0.5, v[14:15] op_sel_hi:[1,0,1]
	v_mul_f32_e32 v2, v7, v7
	v_mul_f32_e32 v3, v9, v9
	v_pk_fma_f32 v[10:11], v[4:5], 0.5, v[16:17] op_sel_hi:[1,0,1]
	v_mul_f32_e32 v4, v13, v13
	v_fmac_f32_e32 v2, v6, v6
	v_fmac_f32_e32 v3, v8, v8
	v_mul_f32_e32 v5, v11, v11
	v_fmac_f32_e32 v4, v12, v12
	v_add_f32_e32 v2, v2, v3
	v_add_f32_e32 v2, v4, v2
	v_fmac_f32_e32 v5, v10, v10
	v_add_f32_e32 v2, v5, v2
	v_add_f32_e32 v2, v20, v2
	ds_bpermute_b32 v3, v123, v2
	v_cvt_pk_bf16_f32 v4, v6, v7
	v_cvt_pk_bf16_f32 v5, v8, v9
	v_cvt_pk_bf16_f32 v6, v12, v13
	v_cvt_pk_bf16_f32 v7, v10, v11
	s_waitcnt lgkmcnt(0)
	v_add_f32_e32 v2, v2, v3
	ds_bpermute_b32 v3, v122, v2
	v_lshl_add_u64 v[8:9], v[50:51], 0, v[138:139]
	global_store_dwordx4 v[8:9], v[4:7], off
	s_and_saveexec_b64 s[44:45], s[0:1]
	s_cbranch_execz .LBB0_219
	v_lshl_add_u64 v[4:5], v[18:19], 2, s[10:11]
	s_waitcnt lgkmcnt(0)
	v_add_f32_e32 v2, v2, v3
	global_atomic_add_f32 v[4:5], v2, off
	global_atomic_add_f32 v[212:213], v214, off
	global_atomic_add_f32 v[212:213], v215, off offset:64
	global_atomic_add_f32 v[212:213], v216, off offset:128
	global_atomic_add_f32 v[212:213], v217, off offset:192
	global_atomic_add_f32 v[212:213], v218, off offset:512
	global_atomic_add_f32 v[212:213], v219, off offset:576
	global_atomic_add_f32 v[212:213], v220, off offset:640
